# P1 and P7 tile boundary: wave groups re-aligned at loop exit (leading group takes one extra barrier) so both groups run the epilogue concurrently; trailing group re-creates the stagger after the epilo
# speedup vs baseline: 1.0141x; 1.0016x over previous
.LBB0_76:
	s_or_b64 exec, exec, s[50:51]
	s_cmpk_lt_u32 s59, 0x100
	s_cbranch_scc1 .Lep_b_80
	s_barrier
.Lep_b_80:
	s_and_b64 vcc, exec, s[42:43]
	s_mov_b32 s30, s0
	s_mov_b32 s50, s44
	s_mov_b64 s[54:55], s[48:49]
	s_mov_b64 s[52:53], s[46:47]
	s_cbranch_vccnz .LBB0_89

.Lpeel_out_80:
	s_cmpk_gt_u32 s59, 0xff
	s_cbranch_scc1 .Lep_a_80
	s_barrier

.LBB0_419:
	v_readlane_b32 s98, v255, 3
	v_readlane_b32 s99, v255, 4
	s_nop 0
	s_cmp_lg_u64 s[98:99], 0
	s_cbranch_scc1 .Lep_b_427
	s_barrier

.Lpeel_out_427:
	v_readlane_b32 s98, v255, 3
	v_readlane_b32 s99, v255, 4
	s_nop 0
	s_cmp_eq_u64 s[98:99], 0
	s_cbranch_scc1 .Lep_a_427
	s_barrier
